# attention: K staged one tile earlier, next tile's K fragments read before the per-tile barrier (no post-barrier LDS latency before QK)
# speedup vs baseline: 1.0019x; 1.0019x over previous
.LBB0_578:
	s_or_b64 exec, exec, s[68:69]
	s_mov_b32 s41, s53
	s_lshl_b64 s[68:69], s[40:41], 10
	s_add_u32 s37, s46, s68
	s_addc_u32 s48, s47, s69
	s_lshl_b32 s3, s22, 1
	s_add_u32 s37, s37, s3
	s_addc_u32 s48, s48, 0
	s_add_u32 s60, s37, 0xab00000
	s_addc_u32 s61, s48, 0
	v_and_b32_e32 v27, 15, v18
	v_lshlrev_b64 v[32:33], 10, v[22:23]
	s_lshl_b32 s52, s22, 16
	v_lshlrev_b32_e32 v176, 4, v27
	v_lshl_add_u64 v[32:33], s[60:61], 0, v[32:33]
	s_add_u32 s37, s42, s52
	v_lshl_add_u64 v[36:37], v[32:33], 0, v[176:177]
	s_mov_b32 s7, 0x8000
	s_addc_u32 s48, s43, 0
	s_lshl_b64 s[70:71], s[40:41], 1
	v_ashrrev_i32_e32 v34, 3, v18
	v_lshl_add_u64 v[30:31], s[60:61], 0, v[16:17]
	v_add_co_u32_e64 v32, s[40:41], s7, v36
	s_add_u32 s62, s37, s70
	v_lshl_add_u64 v[30:31], v[30:31], 0, v[176:177]
	v_addc_co_u32_e64 v33, s[40:41], 0, v37, s[40:41]
	v_ashrrev_i32_e32 v35, 31, v34
	s_addc_u32 s63, s48, s71
	v_and_b32_e32 v29, 7, v18
	flat_load_dwordx4 v[96:99], v[30:31]
	flat_load_dwordx4 v[100:103], v[32:33]
	v_lshlrev_b64 v[32:33], 16, v[34:35]
	v_lshl_add_u64 v[38:39], s[62:63], 0, v[32:33]
	v_lshlrev_b32_e32 v30, 4, v29
	v_mov_b32_e32 v31, v177
	v_lshl_add_u64 v[38:39], v[38:39], 0, v[30:31]
	s_mov_b32 s7, 0xcb00000
	s_mov_b64 s[14:15], 0xcb00000
	v_add_co_u32_e64 v42, s[40:41], s7, v38
	v_lshl_add_u64 v[40:41], v[38:39], 0, s[14:15]
	s_nop 0
	v_addc_co_u32_e64 v43, s[40:41], 0, v39, s[40:41]
	s_mov_b64 s[14:15], 0xcf00000
	s_mov_b32 s7, 0xcf00000
	v_lshl_add_u64 v[44:45], v[38:39], 0, s[14:15]
	v_add_co_u32_e64 v38, s[40:41], s7, v38
	v_readlane_b32 s7, v255, 23
	s_nop 0
	v_addc_co_u32_e64 v39, s[40:41], 0, v39, s[40:41]
	v_add_co_u32_e64 v46, s[40:41], s9, v36
	s_nop 1
	v_addc_co_u32_e64 v47, s[40:41], 0, v37, s[40:41]
	v_add_co_u32_e64 v36, s[40:41], s10, v36
	s_nop 1
	v_addc_co_u32_e64 v37, s[40:41], 0, v37, s[40:41]
	flat_load_dwordx4 v[104:107], v[46:47]
	flat_load_dwordx4 v[108:111], v[36:37]
	flat_load_dwordx4 v[120:123], v[42:43]
	flat_load_dwordx4 v[112:115], v[40:41] offset:128
	flat_load_dwordx4 v[124:127], v[38:39]
	flat_load_dwordx4 v[116:119], v[44:45] offset:128
	v_add_u32_e32 v36, s7, v20
	v_mul_lo_u32 v20, v22, s12
	v_add_u32_e32 v22, v36, v20
	s_waitcnt vmcnt(0) lgkmcnt(0)
	v_lshlrev_b32_e32 v84, 2, v18
	v_add_u32_e32 v84, 0x1ac00, v84
	ds_write_b32 v84, v88
	v_lshlrev_b32_e32 v85, 2, v85
	v_add_u32_e32 v85, 0x1ac00, v85
	ds_write_b32 v85, v89
	ds_write_b128 v22, v[4:7]
	v_mad_u64_u32 v[4:5], s[40:41], v24, s12, v[36:37]
	ds_write_b128 v4, v[0:3]
	v_mad_u64_u32 v[0:1], s[40:41], v26, s12, v[36:37]
	ds_write_b128 v0, v[12:15]
	v_mad_u64_u32 v[0:1], s[40:41], v28, s12, v[36:37]
	ds_write_b128 v0, v[8:11]
	v_lshl_add_u32 v0, v18, 2, 0
	v_add_u32_e32 v1, 0x11800, v0
	ds_write_b32 v1, v21
	s_and_saveexec_b64 s[40:41], vcc
	ds_write_b32 v1, v25 offset:2048
	s_or_b64 exec, exec, s[40:41]
	s_and_saveexec_b64 s[40:41], s[0:1]
	v_add_u32_e32 v0, 0x1a900, v0
	ds_write_b32 v0, v19
	s_or_b64 exec, exec, s[40:41]
	s_ashr_i32 s60, s58, 8
	s_lshl_b32 s0, s60, 7
	s_bfe_u32 s61, s58, 0x20006
	s_add_i32 s1, s0, 0
	v_and_b32_e32 v2, 31, v18
	s_lshl_b32 s37, s61, 5
	s_add_i32 s1, s1, 0x12100
	v_or_b32_e32 v1, s37, v2
	v_mov_b32_e32 v3, s1
	v_lshlrev_b32_e32 v0, 3, v18
	v_mad_u32_u24 v3, v1, s12, v3
	v_add_u32_e32 v1, 0, v20
	s_movk_i32 s1, 0x90
	v_and_b32_e32 v0, 8, v0
	v_add_u32_e32 v239, v1, v176
	v_mul_lo_u32 v1, v34, s1
	v_and_or_b32 v0, v30, s8, v0
	v_add_u32_e32 v1, 0, v1
	v_add_u32_e32 v240, v1, v0
	s_mul_i32 s1, s60, 0x410
	v_mad_u32_u24 v0, v2, s12, 0
	s_add_i32 s62, s1, 0
	s_or_b32 s72, s37, s73
	v_add_u32_e32 v4, s0, v0
	s_lshl_b32 s0, s77, 4
	s_lshr_b32 s59, s58, 6
	s_add_i32 s62, s62, 0x11800
	s_add_i32 s63, s72, 0x9f
	s_addk_i32 s72, 0x5f
	s_and_b32 s0, s0, 0x300
	v_bfe_u32 v236, v18, 5, 1
	v_lshlrev_b32_e32 v1, 7, v2
	s_add_u32 s0, s0, s68
	v_lshlrev_b32_e32 v237, 4, v236
	v_sub_u32_e32 v0, v0, v1
	s_addc_u32 s1, 0, s69
	v_add_u32_e32 v243, v0, v237
	v_lshl_add_u64 v[0:1], s[0:1], 0, v[16:17]
	v_lshl_add_u64 v[0:1], v[0:1], 0, v[176:177]
	v_lshl_add_u64 v[0:1], s[46:47], 0, v[0:1]
	s_mov_b64 s[0:1], 0xab38000
	v_lshl_add_u64 v[190:191], v[0:1], 0, s[0:1]
	v_lshl_add_u64 v[0:1], s[52:53], 0, v[32:33]
	v_mov_b32_e32 v31, v177
	s_add_u32 s0, s42, s70
	v_lshl_add_u64 v[0:1], v[0:1], 0, v[30:31]
	s_addc_u32 s1, s43, s71
	v_lshlrev_b32_e32 v235, 2, v236
	v_lshl_add_u64 v[0:1], s[0:1], 0, v[0:1]
	s_mov_b64 s[0:1], 0xcf00180
	v_lshl_add_u64 v[192:193], v[0:1], 0, s[0:1]
	v_sub_u32_e32 v0, v235, v2
	v_subrev_u32_e32 v0, s37, v0
	s_add_i32 s0, s37, s73
	v_mov_b32_e32 v248, 0
	v_lshlrev_b32_e32 v233, 3, v27
	v_and_b32_e32 v234, 63, v18
	v_add_u32_e32 v241, 0x8800, v240
	v_add_u32_e32 v242, 0xa800, v240
	v_mul_u32_u24_e32 v238, 0x110, v2
	v_add_u32_e32 v244, 0xd000, v243
	v_subrev_u32_e32 v245, s73, v0
	s_mov_b32 s22, 0
	s_sub_i32 s46, 0, s0
	v_add_u32_e32 v246, v4, v237
	v_add_u32_e32 v247, v3, v237
	s_mov_b32 s47, 0
	v_mov_b32_e32 v0, 0
	v_mov_b32_e32 v1, v248
	v_mov_b32_e32 v2, v248
	v_mov_b32_e32 v3, v248
	v_mov_b32_e32 v4, v248
	v_mov_b32_e32 v5, v248
	v_mov_b32_e32 v6, v248
	v_mov_b32_e32 v7, v248
	v_mov_b32_e32 v8, v248
	v_mov_b32_e32 v9, v248
	v_mov_b32_e32 v10, v248
	v_mov_b32_e32 v11, v248
	v_mov_b32_e32 v12, v248
	v_mov_b32_e32 v13, v248
	v_mov_b32_e32 v14, v248
	v_mov_b32_e32 v15, v248
	v_mov_b32_e32 v16, 0
	v_mov_b32_e32 v17, v248
	v_mov_b32_e32 v18, v248
	v_mov_b32_e32 v19, v248
	v_mov_b32_e32 v20, v248
	v_mov_b32_e32 v21, v248
	v_mov_b32_e32 v22, v248
	v_mov_b32_e32 v23, v248
	v_mov_b32_e32 v24, v248
	v_mov_b32_e32 v25, v248
	v_mov_b32_e32 v26, v248
	v_mov_b32_e32 v27, v248
	v_mov_b32_e32 v28, v248
	v_mov_b32_e32 v29, v248
	v_mov_b32_e32 v30, v248
	v_mov_b32_e32 v31, v248
	v_mov_b32_e32 v32, 0
	v_mov_b32_e32 v33, v248
	v_mov_b32_e32 v34, v248
	v_mov_b32_e32 v35, v248
	v_mov_b32_e32 v36, v248
	v_mov_b32_e32 v37, v248
	v_mov_b32_e32 v38, v248
	v_mov_b32_e32 v39, v248
	v_mov_b32_e32 v40, v248
	v_mov_b32_e32 v41, v248
	v_mov_b32_e32 v42, v248
	v_mov_b32_e32 v43, v248
	v_mov_b32_e32 v44, v248
	v_mov_b32_e32 v45, v248
	v_mov_b32_e32 v46, v248
	v_mov_b32_e32 v47, v248
	v_mov_b32_e32 v48, 0
	v_mov_b32_e32 v49, v248
	v_mov_b32_e32 v50, v248
	v_mov_b32_e32 v51, v248
	v_mov_b32_e32 v52, v248
	v_mov_b32_e32 v53, v248
	v_mov_b32_e32 v54, v248
	v_mov_b32_e32 v55, v248
	v_mov_b32_e32 v56, v248
	v_mov_b32_e32 v57, v248
	v_mov_b32_e32 v58, v248
	v_mov_b32_e32 v59, v248
	v_mov_b32_e32 v60, v248
	v_mov_b32_e32 v61, v248
	v_mov_b32_e32 v62, v248
	v_mov_b32_e32 v63, v248
	ds_write_b128 v239, v[96:99]
	ds_write_b128 v239, v[100:103] offset:8704
	ds_write2_b64 v241, v[120:121], v[122:123] offset1:2
	ds_write2_b64 v242, v[124:125], v[126:127] offset0:128 offset1:130
	ds_write_b128 v239, v[104:107] offset:17408
	ds_write_b128 v239, v[108:111] offset:26112
	s_waitcnt lgkmcnt(0)
	s_barrier
	ds_read_b128 v[222:225], v247
	ds_read_b128 v[218:221], v247 offset:32
	ds_read_b128 v[214:217], v247 offset:64
	ds_read_b128 v[210:213], v247 offset:96
	ds_read_b128 v[172:175], v246 offset:0
	ds_read_b128 v[168:171], v246 offset:32
	ds_read_b128 v[164:167], v246 offset:64
	ds_read_b128 v[160:163], v246 offset:96
	ds_read_b128 v[156:159], v246 offset:8704
	ds_read_b128 v[152:155], v246 offset:8736
	ds_read_b128 v[148:151], v246 offset:8768
	ds_read_b128 v[144:147], v246 offset:8800
	v_add_co_u32_e32 v186, vcc, 0xfffe8000, v190
	s_nop 1
	v_addc_co_u32_e32 v187, vcc, -1, v191, vcc
	global_load_dwordx4 v[104:107], v[186:187], off
	v_add_co_u32_e32 v186, vcc, 0xffff0000, v190
	s_nop 1
	v_addc_co_u32_e32 v187, vcc, -1, v191, vcc
	global_load_dwordx4 v[108:111], v[186:187], off
	s_mov_b32 s100, -1
	s_branch .LBB0_584
.LBB0_583:
	s_waitcnt lgkmcnt(8)
	s_barrier
	s_add_i32 s47, s47, 2
	v_lshl_add_u64 v[190:191], v[190:191], 0, s[84:85]
	v_lshl_add_u64 v[192:193], v[192:193], 0, s[26:27]
	s_addk_i32 s22, 0x80
	s_and_b64 vcc, exec, s[0:1]
	s_cbranch_vccnz .LBB0_598

.LBB0_586:
	s_add_i32 s68, s46, s22
	s_setprio 1
	s_cmp_lt_u32 s22, s63
	s_cselect_b64 s[42:43], -1, 0
	s_cmpk_gt_i32 s68, 0xff41
	s_cselect_b64 s[70:71], -1, 0
	s_and_b64 s[70:71], s[42:43], s[70:71]
	s_and_b64 vcc, exec, s[70:71]
	s_cbranch_vccnz .La1t0_near
	s_and_b64 s[42:43], s[42:43], exec
	s_cselect_b32 s42, 0, 0x400
	s_add_i32 s42, s62, s42
	s_cmp_eq_u32 s42, s100
	s_cbranch_scc1 .La1t0_cb
	v_mov_b32_e32 v251, s42
	ds_read_b32 v251, v251
	s_mov_b32 s100, s42
	s_waitcnt lgkmcnt(0)
	v_mov_b32_e32 v194, v251
	v_mov_b32_e32 v195, v251
	v_mov_b32_e32 v196, v251
	v_mov_b32_e32 v197, v251
	v_mov_b32_e32 v198, v251
	v_mov_b32_e32 v199, v251
	v_mov_b32_e32 v200, v251
	v_mov_b32_e32 v201, v251
	v_mov_b32_e32 v202, v251
	v_mov_b32_e32 v203, v251
	v_mov_b32_e32 v204, v251
	v_mov_b32_e32 v205, v251
	v_mov_b32_e32 v206, v251
	v_mov_b32_e32 v207, v251
	v_mov_b32_e32 v208, v251
	v_mov_b32_e32 v209, v251
	s_nop 1
.La1t0_cb:
	v_add_u32_e32 v249, s22, v245
	ds_read_b128 v[128:131], v243 offset:44032
	ds_read_b128 v[132:135], v243 offset:44064
	ds_read_b128 v[136:139], v243 offset:48640
	ds_read_b128 v[140:143], v243 offset:48672
	s_cmp_eq_u64 s[40:41], 0
	s_waitcnt lgkmcnt(11)
	v_mfma_f32_32x32x16_bf16 v[64:79], v[172:175], v[222:225], v[194:209]
	s_cbranch_scc1 .La1t0_nl0
	v_add_co_u32_e32 v186, vcc, 0xffff8000, v190
	s_nop 1
	v_addc_co_u32_e32 v187, vcc, -1, v191, vcc
	global_load_dwordx4 v[96:99], v[186:187], off
.La1t0_nl0:
	s_waitcnt lgkmcnt(10)
	v_mfma_f32_32x32x16_bf16 v[64:79], v[168:171], v[218:221], v[64:79]
	s_cbranch_scc1 .La1t0_nl1
	global_load_dwordx4 v[100:103], v[190:191], off

.La1t0_lv_b:
	v_add_u32_e32 v251, 0xd000, v240
	ds_write_b128 v239, v[104:107]
	ds_write_b128 v239, v[108:111] offset:8704
	ds_write2_b64 v251, v[112:113], v[114:115] offset1:2
	v_add_u32_e32 v251, 0xf000, v240
	ds_write2_b64 v251, v[116:117], v[118:119] offset0:128 offset1:130
	v_exp_f32_e32 v84, v84
	v_exp_f32_e32 v85, v85
	v_exp_f32_e32 v86, v86
	s_waitcnt lgkmcnt(6)
	v_mfma_f32_32x32x16_bf16 v[16:31], v[132:135], v[164:167], v[16:31]
	ds_read_b128 v[128:131], v243 offset:44096
	ds_read_b128 v[132:135], v243 offset:44128
	v_exp_f32_e32 v87, v87
	v_exp_f32_e32 v88, v88
	v_exp_f32_e32 v89, v89
	s_waitcnt lgkmcnt(7)
	v_mfma_f32_32x32x16_bf16 v[0:15], v[136:139], v[160:163], v[0:15]
	v_exp_f32_e32 v90, v90
	v_exp_f32_e32 v91, v91
	v_exp_f32_e32 v92, v92
	s_waitcnt lgkmcnt(6)
	v_mfma_f32_32x32x16_bf16 v[0:15], v[140:143], v[164:167], v[0:15]
	ds_read_b128 v[136:139], v243 offset:48704
	ds_read_b128 v[140:143], v243 offset:48736
	v_exp_f32_e32 v93, v93
	v_exp_f32_e32 v94, v94
	v_exp_f32_e32 v95, v95
	s_waitcnt lgkmcnt(7)
	v_mfma_f32_32x32x16_bf16 v[48:63], v[144:147], v[160:163], v[48:63]
	v_cvt_pk_bf16_f32 v168, v80, v81
	v_cvt_pk_bf16_f32 v169, v82, v83
	s_waitcnt lgkmcnt(6)
	v_mfma_f32_32x32x16_bf16 v[48:63], v[148:151], v[164:167], v[48:63]
	ds_read_b128 v[144:147], v243 offset:34880
	ds_read_b128 v[148:151], v243 offset:34912
	v_cvt_pk_bf16_f32 v170, v84, v85
	v_cvt_pk_bf16_f32 v171, v86, v87
	s_waitcnt lgkmcnt(7)
	v_mfma_f32_32x32x16_bf16 v[32:47], v[152:155], v[160:163], v[32:47]
	v_cvt_pk_bf16_f32 v172, v88, v89
	v_cvt_pk_bf16_f32 v173, v90, v91
	s_waitcnt lgkmcnt(6)
	v_mfma_f32_32x32x16_bf16 v[32:47], v[156:159], v[164:167], v[32:47]
	ds_read_b128 v[152:155], v243 offset:39488
	ds_read_b128 v[156:159], v243 offset:39520
	v_cvt_pk_bf16_f32 v174, v92, v93
	v_cvt_pk_bf16_f32 v175, v94, v95
	s_nop 1
	s_waitcnt lgkmcnt(7)
	v_mfma_f32_32x32x16_bf16 v[16:31], v[128:131], v[168:171], v[16:31]
	v_add_f32_e32 v186, v64, v67
	v_add_f32_e32 v187, v65, v68
	v_add_f32_e32 v251, v66, v69
	v_add_f32_e32 v186, v186, v70
	v_add_f32_e32 v187, v187, v71
	s_waitcnt lgkmcnt(6)
	v_mfma_f32_32x32x16_bf16 v[16:31], v[132:135], v[172:175], v[16:31]
	v_add_f32_e32 v251, v251, v72
	v_add_f32_e32 v186, v186, v73
	v_add_f32_e32 v187, v187, v74
	v_add_f32_e32 v251, v251, v75
	v_add_f32_e32 v186, v186, v76
	s_waitcnt lgkmcnt(5)
	v_mfma_f32_32x32x16_bf16 v[0:15], v[136:139], v[168:171], v[0:15]
	v_add_f32_e32 v187, v187, v77
	v_add_f32_e32 v251, v251, v78
	v_add_f32_e32 v186, v186, v79
	v_add_f32_e32 v187, v187, v80
	v_add_f32_e32 v251, v251, v81
	s_waitcnt lgkmcnt(4)
	v_mfma_f32_32x32x16_bf16 v[0:15], v[140:143], v[172:175], v[0:15]
	v_add_f32_e32 v186, v186, v82
	v_add_f32_e32 v187, v187, v83
	v_add_f32_e32 v251, v251, v84
	v_add_f32_e32 v186, v186, v85
	v_add_f32_e32 v187, v187, v86
	s_waitcnt lgkmcnt(3)
	v_mfma_f32_32x32x16_bf16 v[48:63], v[144:147], v[168:171], v[48:63]
	v_add_f32_e32 v251, v251, v87
	v_add_f32_e32 v186, v186, v88
	v_add_f32_e32 v187, v187, v89
	v_add_f32_e32 v251, v251, v90
	v_add_f32_e32 v186, v186, v91
	s_waitcnt lgkmcnt(2)
	v_mfma_f32_32x32x16_bf16 v[48:63], v[148:151], v[172:175], v[48:63]
	v_add_f32_e32 v187, v187, v92
	v_add_f32_e32 v251, v251, v93
	v_add_f32_e32 v186, v186, v94
	v_add_f32_e32 v187, v187, v95
	v_add_f32_e32 v186, v186, v187
	s_waitcnt lgkmcnt(1)
	v_mfma_f32_32x32x16_bf16 v[32:47], v[152:155], v[168:171], v[32:47]
	v_add_f32_e32 v186, v186, v251
	v_add_f32_e32 v248, v248, v186
	s_waitcnt lgkmcnt(0)
	v_mfma_f32_32x32x16_bf16 v[32:47], v[156:159], v[172:175], v[32:47]
	s_setprio 0
	ds_read_b128 v[172:175], v246 offset:17408
	ds_read_b128 v[168:171], v246 offset:17440
	ds_read_b128 v[164:167], v246 offset:17472
	ds_read_b128 v[160:163], v246 offset:17504
	ds_read_b128 v[156:159], v246 offset:26112
	ds_read_b128 v[152:155], v246 offset:26144
	ds_read_b128 v[148:151], v246 offset:26176
	ds_read_b128 v[144:147], v246 offset:26208
	s_branch .La1t0_pw
.La1t0_near:
	v_add_u32_e32 v249, s22, v245
	s_mul_i32 s101, s60, 0x704
	s_add_i32 s101, s101, 0x1af80
	v_lshl_add_u32 v251, v249, 2, s101
	ds_read_b32 v64, v251 offset:0
	ds_read_b32 v65, v251 offset:4
	ds_read_b32 v66, v251 offset:8
	ds_read_b32 v67, v251 offset:12
	ds_read_b32 v68, v251 offset:32
	ds_read_b32 v69, v251 offset:36
	ds_read_b32 v70, v251 offset:40
	ds_read_b32 v71, v251 offset:44
	ds_read_b32 v72, v251 offset:64
	ds_read_b32 v73, v251 offset:68
	ds_read_b32 v74, v251 offset:72
	ds_read_b32 v75, v251 offset:76
	ds_read_b32 v76, v251 offset:96
	ds_read_b32 v77, v251 offset:100
	ds_read_b32 v78, v251 offset:104
	ds_read_b32 v79, v251 offset:108
	ds_read_b32 v80, v251 offset:128
	ds_read_b32 v81, v251 offset:132
	ds_read_b32 v82, v251 offset:136
	ds_read_b32 v83, v251 offset:140
	ds_read_b32 v84, v251 offset:160
	ds_read_b32 v85, v251 offset:164
	ds_read_b32 v86, v251 offset:168
	ds_read_b32 v87, v251 offset:172
	ds_read_b32 v88, v251 offset:192
	ds_read_b32 v89, v251 offset:196
	ds_read_b32 v90, v251 offset:200
	ds_read_b32 v91, v251 offset:204
	ds_read_b32 v92, v251 offset:224
	ds_read_b32 v93, v251 offset:228
	ds_read_b32 v94, v251 offset:232
	ds_read_b32 v95, v251 offset:236
	s_waitcnt lgkmcnt(0)
	ds_read_b128 v[128:131], v243 offset:44032
	ds_read_b128 v[132:135], v243 offset:44064
	ds_read_b128 v[136:139], v243 offset:48640
	ds_read_b128 v[140:143], v243 offset:48672
	s_cmp_eq_u64 s[40:41], 0
	v_mfma_f32_32x32x16_bf16 v[64:79], v[172:175], v[222:225], v[64:79]
	s_cbranch_scc1 .La1t0n_nl0
	v_add_co_u32_e32 v186, vcc, 0xffff8000, v190
	s_nop 1
	v_addc_co_u32_e32 v187, vcc, -1, v191, vcc
	global_load_dwordx4 v[96:99], v[186:187], off
.La1t0n_nl0:
	v_mfma_f32_32x32x16_bf16 v[64:79], v[168:171], v[218:221], v[64:79]
	s_cbranch_scc1 .La1t0n_nl1
	global_load_dwordx4 v[100:103], v[190:191], off

.La1t0_pw:
	s_waitcnt lgkmcnt(8)
	s_barrier
	s_cmp_gt_u32 s47, 28
	s_cbranch_scc1 .LBB0_592
.LBB0_592:
	s_setprio 1
	s_cmp_lt_u32 s22, s72
	s_cselect_b64 s[42:43], -1, 0
	s_cmpk_gt_i32 s68, 0xff01
	s_cselect_b64 s[68:69], -1, 0
	s_and_b64 s[68:69], s[42:43], s[68:69]
	s_and_b64 vcc, exec, s[68:69]
	s_cbranch_vccnz .La1t1_near
	s_and_b64 s[42:43], s[42:43], exec
	s_cselect_b32 s42, 0, 0x400
	s_add_i32 s42, s62, s42
	s_cmp_eq_u32 s42, s100
	s_cbranch_scc1 .La1t1_cb
	v_mov_b32_e32 v251, s42
	ds_read_b32 v251, v251
	s_mov_b32 s100, s42
	s_waitcnt lgkmcnt(0)
	v_mov_b32_e32 v194, v251
	v_mov_b32_e32 v195, v251
	v_mov_b32_e32 v196, v251
	v_mov_b32_e32 v197, v251
	v_mov_b32_e32 v198, v251
	v_mov_b32_e32 v199, v251
	v_mov_b32_e32 v200, v251
	v_mov_b32_e32 v201, v251
	v_mov_b32_e32 v202, v251
	v_mov_b32_e32 v203, v251
	v_mov_b32_e32 v204, v251
	v_mov_b32_e32 v205, v251
	v_mov_b32_e32 v206, v251
	v_mov_b32_e32 v207, v251
	v_mov_b32_e32 v208, v251
	v_mov_b32_e32 v209, v251
	s_nop 1
.La1t1_cb:
	ds_read_b128 v[128:131], v243 offset:62464
	ds_read_b128 v[132:135], v243 offset:62496
	ds_read_b128 v[136:139], v244 offset:13824
	ds_read_b128 v[140:143], v244 offset:13856
	s_cmp_eq_u64 s[40:41], 0
	s_waitcnt lgkmcnt(11)
	v_mfma_f32_32x32x16_bf16 v[64:79], v[172:175], v[222:225], v[194:209]
	s_cbranch_scc1 .La1t1_nl0
	v_add_co_u32_e32 v186, vcc, 0x8000, v190
	s_nop 1
	v_addc_co_u32_e32 v187, vcc, 0, v191, vcc
	global_load_dwordx4 v[104:107], v[186:187], off
.La1t1_nl0:
	s_waitcnt lgkmcnt(10)
	v_mfma_f32_32x32x16_bf16 v[64:79], v[168:171], v[218:221], v[64:79]
	s_cbranch_scc1 .La1t1_nl1
	v_add_co_u32_e32 v186, vcc, 0x10000, v190
	s_nop 1
	v_addc_co_u32_e32 v187, vcc, 0, v191, vcc
	global_load_dwordx4 v[108:111], v[186:187], off

.La1t1_nl3:
	s_waitcnt lgkmcnt(7)
	v_mfma_f32_32x32x16_bf16 v[80:95], v[156:159], v[222:225], v[194:209]
	s_nop 11
	v_exp_f32_e32 v64, v64
	v_exp_f32_e32 v65, v65
	v_exp_f32_e32 v66, v66
	v_exp_f32_e32 v67, v67
	v_exp_f32_e32 v68, v68
	v_exp_f32_e32 v69, v69
	s_waitcnt lgkmcnt(6)
	v_mfma_f32_32x32x16_bf16 v[80:95], v[152:155], v[218:221], v[80:95]
	v_exp_f32_e32 v70, v70
	v_exp_f32_e32 v71, v71
	v_exp_f32_e32 v72, v72
	v_exp_f32_e32 v73, v73
	v_exp_f32_e32 v74, v74
	v_exp_f32_e32 v75, v75
	s_waitcnt lgkmcnt(5)
	v_mfma_f32_32x32x16_bf16 v[80:95], v[148:151], v[214:217], v[80:95]
	v_exp_f32_e32 v76, v76
	v_exp_f32_e32 v77, v77
	v_exp_f32_e32 v78, v78
	v_exp_f32_e32 v79, v79
	v_cvt_pk_bf16_f32 v160, v64, v65
	v_cvt_pk_bf16_f32 v161, v66, v67
	s_waitcnt lgkmcnt(4)
	v_mfma_f32_32x32x16_bf16 v[80:95], v[144:147], v[210:213], v[80:95]
	ds_read_b128 v[144:147], v243 offset:53248
	ds_read_b128 v[148:151], v243 offset:53280
	ds_read_b128 v[152:155], v243 offset:57856
	ds_read_b128 v[156:159], v243 offset:57888
	v_cvt_pk_bf16_f32 v162, v68, v69
	v_cvt_pk_bf16_f32 v163, v70, v71
	v_cvt_pk_bf16_f32 v164, v72, v73
	v_cvt_pk_bf16_f32 v165, v74, v75
	v_cvt_pk_bf16_f32 v166, v76, v77
	v_cvt_pk_bf16_f32 v167, v78, v79
	s_nop 4
	v_exp_f32_e32 v80, v80
	v_exp_f32_e32 v81, v81
	v_exp_f32_e32 v82, v82
	v_exp_f32_e32 v83, v83
	s_waitcnt lgkmcnt(7)
	v_mfma_f32_32x32x16_bf16 v[16:31], v[128:131], v[160:163], v[16:31]
	s_cmp_eq_u64 s[40:41], 0
	s_cbranch_scc1 .La1t1_lv_s
	s_waitcnt vmcnt(4)
	ds_write_b128 v239, v[96:99] offset:17408
	ds_write_b128 v239, v[100:103] offset:26112
	ds_write2_b64 v241, v[120:121], v[122:123] offset1:2
	ds_write2_b64 v242, v[124:125], v[126:127] offset0:128 offset1:130
.La1t1_lv_s:
	v_exp_f32_e32 v84, v84
	v_exp_f32_e32 v85, v85
	v_exp_f32_e32 v86, v86
	s_waitcnt lgkmcnt(6)
	v_mfma_f32_32x32x16_bf16 v[16:31], v[132:135], v[164:167], v[16:31]
	ds_read_b128 v[128:131], v243 offset:62528
	ds_read_b128 v[132:135], v243 offset:62560
	v_exp_f32_e32 v87, v87
	v_exp_f32_e32 v88, v88
	v_exp_f32_e32 v89, v89
	s_waitcnt lgkmcnt(7)
	v_mfma_f32_32x32x16_bf16 v[0:15], v[136:139], v[160:163], v[0:15]
	v_exp_f32_e32 v90, v90
	v_exp_f32_e32 v91, v91
	v_exp_f32_e32 v92, v92
	s_waitcnt lgkmcnt(6)
	v_mfma_f32_32x32x16_bf16 v[0:15], v[140:143], v[164:167], v[0:15]
	ds_read_b128 v[136:139], v244 offset:13888
	ds_read_b128 v[140:143], v244 offset:13920
	v_exp_f32_e32 v93, v93
	v_exp_f32_e32 v94, v94
	v_exp_f32_e32 v95, v95
	s_waitcnt lgkmcnt(7)
	v_mfma_f32_32x32x16_bf16 v[48:63], v[144:147], v[160:163], v[48:63]
	v_cvt_pk_bf16_f32 v168, v80, v81
	v_cvt_pk_bf16_f32 v169, v82, v83
	s_waitcnt lgkmcnt(6)
	v_mfma_f32_32x32x16_bf16 v[48:63], v[148:151], v[164:167], v[48:63]
	ds_read_b128 v[144:147], v243 offset:53312
	ds_read_b128 v[148:151], v243 offset:53344
	v_cvt_pk_bf16_f32 v170, v84, v85
	v_cvt_pk_bf16_f32 v171, v86, v87
	s_waitcnt lgkmcnt(7)
	v_mfma_f32_32x32x16_bf16 v[32:47], v[152:155], v[160:163], v[32:47]
	v_cvt_pk_bf16_f32 v172, v88, v89
	v_cvt_pk_bf16_f32 v173, v90, v91
	s_waitcnt lgkmcnt(6)
	v_mfma_f32_32x32x16_bf16 v[32:47], v[156:159], v[164:167], v[32:47]
	ds_read_b128 v[152:155], v243 offset:57920
	ds_read_b128 v[156:159], v243 offset:57952
	v_cvt_pk_bf16_f32 v174, v92, v93
	v_cvt_pk_bf16_f32 v175, v94, v95
	s_nop 1
	s_waitcnt lgkmcnt(7)
	v_mfma_f32_32x32x16_bf16 v[16:31], v[128:131], v[168:171], v[16:31]
	v_add_f32_e32 v186, v64, v67
	v_add_f32_e32 v187, v65, v68
	v_add_f32_e32 v251, v66, v69
	v_add_f32_e32 v186, v186, v70
	v_add_f32_e32 v187, v187, v71
	s_waitcnt lgkmcnt(6)
	v_mfma_f32_32x32x16_bf16 v[16:31], v[132:135], v[172:175], v[16:31]
	v_add_f32_e32 v251, v251, v72
	v_add_f32_e32 v186, v186, v73
	v_add_f32_e32 v187, v187, v74
	v_add_f32_e32 v251, v251, v75
	v_add_f32_e32 v186, v186, v76
	s_waitcnt lgkmcnt(5)
	v_mfma_f32_32x32x16_bf16 v[0:15], v[136:139], v[168:171], v[0:15]
	v_add_f32_e32 v187, v187, v77
	v_add_f32_e32 v251, v251, v78
	v_add_f32_e32 v186, v186, v79
	v_add_f32_e32 v187, v187, v80
	v_add_f32_e32 v251, v251, v81
	s_waitcnt lgkmcnt(4)
	v_mfma_f32_32x32x16_bf16 v[0:15], v[140:143], v[172:175], v[0:15]
	v_add_f32_e32 v186, v186, v82
	v_add_f32_e32 v187, v187, v83
	v_add_f32_e32 v251, v251, v84
	v_add_f32_e32 v186, v186, v85
	v_add_f32_e32 v187, v187, v86
	s_waitcnt lgkmcnt(3)
	v_mfma_f32_32x32x16_bf16 v[48:63], v[144:147], v[168:171], v[48:63]
	v_add_f32_e32 v251, v251, v87
	v_add_f32_e32 v186, v186, v88
	v_add_f32_e32 v187, v187, v89
	v_add_f32_e32 v251, v251, v90
	v_add_f32_e32 v186, v186, v91
	s_waitcnt lgkmcnt(2)
	v_mfma_f32_32x32x16_bf16 v[48:63], v[148:151], v[172:175], v[48:63]
	v_add_f32_e32 v187, v187, v92
	v_add_f32_e32 v251, v251, v93
	v_add_f32_e32 v186, v186, v94
	v_add_f32_e32 v187, v187, v95
	v_add_f32_e32 v186, v186, v187
	s_waitcnt lgkmcnt(1)
	v_mfma_f32_32x32x16_bf16 v[32:47], v[152:155], v[168:171], v[32:47]
	v_add_f32_e32 v186, v186, v251
	v_add_f32_e32 v248, v248, v186
	s_waitcnt lgkmcnt(0)
	v_mfma_f32_32x32x16_bf16 v[32:47], v[156:159], v[172:175], v[32:47]
	s_setprio 0
	ds_read_b128 v[172:175], v246 offset:0
	ds_read_b128 v[168:171], v246 offset:32
	ds_read_b128 v[164:167], v246 offset:64
	ds_read_b128 v[160:163], v246 offset:96
	ds_read_b128 v[156:159], v246 offset:8704
	ds_read_b128 v[152:155], v246 offset:8736
	ds_read_b128 v[148:151], v246 offset:8768
	ds_read_b128 v[144:147], v246 offset:8800
	s_branch .LBB0_583
.La1t1_near:
	s_mul_i32 s101, s60, 0x704
	s_add_i32 s101, s101, 0x1b080
	v_lshl_add_u32 v251, v249, 2, s101
	ds_read_b32 v64, v251 offset:0
	ds_read_b32 v65, v251 offset:4
	ds_read_b32 v66, v251 offset:8
	ds_read_b32 v67, v251 offset:12
	ds_read_b32 v68, v251 offset:32
	ds_read_b32 v69, v251 offset:36
	ds_read_b32 v70, v251 offset:40
	ds_read_b32 v71, v251 offset:44
	ds_read_b32 v72, v251 offset:64
	ds_read_b32 v73, v251 offset:68
	ds_read_b32 v74, v251 offset:72
	ds_read_b32 v75, v251 offset:76
	ds_read_b32 v76, v251 offset:96
	ds_read_b32 v77, v251 offset:100
	ds_read_b32 v78, v251 offset:104
	ds_read_b32 v79, v251 offset:108
	ds_read_b32 v80, v251 offset:128
	ds_read_b32 v81, v251 offset:132
	ds_read_b32 v82, v251 offset:136
	ds_read_b32 v83, v251 offset:140
	ds_read_b32 v84, v251 offset:160
	ds_read_b32 v85, v251 offset:164
	ds_read_b32 v86, v251 offset:168
	ds_read_b32 v87, v251 offset:172
	ds_read_b32 v88, v251 offset:192
	ds_read_b32 v89, v251 offset:196
	ds_read_b32 v90, v251 offset:200
	ds_read_b32 v91, v251 offset:204
	ds_read_b32 v92, v251 offset:224
	ds_read_b32 v93, v251 offset:228
	ds_read_b32 v94, v251 offset:232
	ds_read_b32 v95, v251 offset:236
	s_waitcnt lgkmcnt(0)
	ds_read_b128 v[128:131], v243 offset:62464
	ds_read_b128 v[132:135], v243 offset:62496
	ds_read_b128 v[136:139], v244 offset:13824
	ds_read_b128 v[140:143], v244 offset:13856
	s_cmp_eq_u64 s[40:41], 0
	v_mfma_f32_32x32x16_bf16 v[64:79], v[172:175], v[222:225], v[64:79]
	s_cbranch_scc1 .La1t1n_nl0
	v_add_co_u32_e32 v186, vcc, 0x8000, v190
	s_nop 1
	v_addc_co_u32_e32 v187, vcc, 0, v191, vcc
	global_load_dwordx4 v[104:107], v[186:187], off
.La1t1n_nl0:
	v_mfma_f32_32x32x16_bf16 v[64:79], v[168:171], v[218:221], v[64:79]
	s_cbranch_scc1 .La1t1n_nl1
	v_add_co_u32_e32 v186, vcc, 0x10000, v190
	s_nop 1
	v_addc_co_u32_e32 v187, vcc, 0, v191, vcc
	global_load_dwordx4 v[108:111], v[186:187], off

.La1t1n_nl3:
	v_mfma_f32_32x32x16_bf16 v[80:95], v[156:159], v[222:225], v[80:95]
	s_nop 11
	v_exp_f32_e32 v64, v64
	v_exp_f32_e32 v65, v65
	v_exp_f32_e32 v66, v66
	v_exp_f32_e32 v67, v67
	v_exp_f32_e32 v68, v68
	v_exp_f32_e32 v69, v69
	v_mfma_f32_32x32x16_bf16 v[80:95], v[152:155], v[218:221], v[80:95]
	v_exp_f32_e32 v70, v70
	v_exp_f32_e32 v71, v71
	v_exp_f32_e32 v72, v72
	v_exp_f32_e32 v73, v73
	v_exp_f32_e32 v74, v74
	v_exp_f32_e32 v75, v75
	v_mfma_f32_32x32x16_bf16 v[80:95], v[148:151], v[214:217], v[80:95]
	v_exp_f32_e32 v76, v76
	v_exp_f32_e32 v77, v77
	v_exp_f32_e32 v78, v78
	v_exp_f32_e32 v79, v79
	v_cvt_pk_bf16_f32 v160, v64, v65
	v_cvt_pk_bf16_f32 v161, v66, v67
	v_mfma_f32_32x32x16_bf16 v[80:95], v[144:147], v[210:213], v[80:95]
	ds_read_b128 v[144:147], v243 offset:53248
	ds_read_b128 v[148:151], v243 offset:53280
	ds_read_b128 v[152:155], v243 offset:57856
	ds_read_b128 v[156:159], v243 offset:57888
	v_cvt_pk_bf16_f32 v162, v68, v69
	v_cvt_pk_bf16_f32 v163, v70, v71
	v_cvt_pk_bf16_f32 v164, v72, v73
	v_cvt_pk_bf16_f32 v165, v74, v75
	v_cvt_pk_bf16_f32 v166, v76, v77
	v_cvt_pk_bf16_f32 v167, v78, v79
	s_nop 4
	v_exp_f32_e32 v80, v80
	v_exp_f32_e32 v81, v81
	v_exp_f32_e32 v82, v82
	v_exp_f32_e32 v83, v83
	s_waitcnt lgkmcnt(7)
	v_mfma_f32_32x32x16_bf16 v[16:31], v[128:131], v[160:163], v[16:31]
	s_cmp_eq_u64 s[40:41], 0
	s_cbranch_scc1 .La1t1n_lv_s
	s_waitcnt vmcnt(4)
	ds_write_b128 v239, v[96:99] offset:17408
	ds_write_b128 v239, v[100:103] offset:26112
	ds_write2_b64 v241, v[120:121], v[122:123] offset1:2
	ds_write2_b64 v242, v[124:125], v[126:127] offset0:128 offset1:130

.LBB0_598:
	s_waitcnt lgkmcnt(0)
	v_lshlrev_b32_e32 v64, 2, v234
	v_xor_b32_e32 v67, 0x80, v64
	ds_bpermute_b32 v65, v67, v248
	s_lshl_b32 s0, s61, 14
	s_add_i32 s0, s0, 0
	s_cmp_eq_u32 s60, 1
	v_add_u32_e32 v64, s0, v64
	s_waitcnt lgkmcnt(0)
	v_add_f32_e32 v65, v248, v65
	s_cbranch_scc0 .LBB0_600
	v_div_scale_f32 v66, s[0:1], v65, v65, s74
	v_rcp_f32_e32 v68, v66
	v_div_scale_f32 v69, vcc, s74, v65, s74
	v_fma_f32 v70, -v66, v68, 1.0
	v_fmac_f32_e32 v68, v70, v68
	v_mul_f32_e32 v70, v69, v68
	v_fma_f32 v71, -v66, v70, v69
	v_fmac_f32_e32 v70, v71, v68
	v_fma_f32 v66, -v66, v70, v69
	v_div_fmas_f32 v66, v66, v68, v70
	v_div_fixup_f32 v66, v66, v65, s74
	v_mul_f32_e32 v68, v48, v66
	v_mul_f32_e32 v69, v49, v66
	ds_write2st64_b32 v64, v68, v69 offset1:1
	v_mul_f32_e32 v68, v50, v66
	v_mul_f32_e32 v69, v51, v66
	ds_write2st64_b32 v64, v68, v69 offset0:2 offset1:3
	v_mul_f32_e32 v68, v52, v66
	v_mul_f32_e32 v69, v53, v66
	ds_write2st64_b32 v64, v68, v69 offset0:4 offset1:5
	v_mul_f32_e32 v68, v54, v66
	v_mul_f32_e32 v69, v55, v66
	ds_write2st64_b32 v64, v68, v69 offset0:6 offset1:7
	v_mul_f32_e32 v68, v56, v66
	v_mul_f32_e32 v69, v57, v66
	ds_write2st64_b32 v64, v68, v69 offset0:8 offset1:9
	v_mul_f32_e32 v68, v58, v66
	v_mul_f32_e32 v69, v59, v66
	ds_write2st64_b32 v64, v68, v69 offset0:10 offset1:11
	v_mul_f32_e32 v68, v60, v66
	v_mul_f32_e32 v69, v61, v66
	ds_write2st64_b32 v64, v68, v69 offset0:12 offset1:13
	v_mul_f32_e32 v68, v62, v66
	v_mul_f32_e32 v69, v63, v66
	ds_write2st64_b32 v64, v68, v69 offset0:14 offset1:15
	v_mul_f32_e32 v68, v32, v66
	v_mul_f32_e32 v69, v33, v66
	ds_write2st64_b32 v64, v68, v69 offset0:16 offset1:17
	v_mul_f32_e32 v68, v34, v66
	v_mul_f32_e32 v69, v35, v66
	ds_write2st64_b32 v64, v68, v69 offset0:18 offset1:19
	v_mul_f32_e32 v68, v36, v66
	v_mul_f32_e32 v69, v37, v66
	ds_write2st64_b32 v64, v68, v69 offset0:20 offset1:21
	v_mul_f32_e32 v68, v38, v66
	v_mul_f32_e32 v69, v39, v66
	ds_write2st64_b32 v64, v68, v69 offset0:22 offset1:23
	v_mul_f32_e32 v68, v40, v66
	v_mul_f32_e32 v69, v41, v66
	ds_write2st64_b32 v64, v68, v69 offset0:24 offset1:25
	v_mul_f32_e32 v68, v42, v66
	v_mul_f32_e32 v69, v43, v66
	ds_write2st64_b32 v64, v68, v69 offset0:26 offset1:27
	v_mul_f32_e32 v68, v44, v66
	v_mul_f32_e32 v69, v45, v66
	ds_write2st64_b32 v64, v68, v69 offset0:28 offset1:29
	v_mul_f32_e32 v68, v46, v66
	v_mul_f32_e32 v69, v47, v66
	ds_write2st64_b32 v64, v68, v69 offset0:30 offset1:31
	v_mul_f32_e32 v68, v16, v66
	v_mul_f32_e32 v69, v17, v66
	ds_write2st64_b32 v64, v68, v69 offset0:32 offset1:33
	v_mul_f32_e32 v68, v18, v66
	v_mul_f32_e32 v69, v19, v66
	ds_write2st64_b32 v64, v68, v69 offset0:34 offset1:35
	v_mul_f32_e32 v68, v20, v66
	v_mul_f32_e32 v69, v21, v66
	ds_write2st64_b32 v64, v68, v69 offset0:36 offset1:37
	v_mul_f32_e32 v68, v22, v66
	v_mul_f32_e32 v69, v23, v66
	ds_write2st64_b32 v64, v68, v69 offset0:38 offset1:39
	v_mul_f32_e32 v68, v24, v66
	v_mul_f32_e32 v69, v25, v66
	ds_write2st64_b32 v64, v68, v69 offset0:40 offset1:41
	v_mul_f32_e32 v68, v26, v66
	v_mul_f32_e32 v69, v27, v66
	ds_write2st64_b32 v64, v68, v69 offset0:42 offset1:43
	v_mul_f32_e32 v68, v28, v66
	v_mul_f32_e32 v69, v29, v66
	ds_write2st64_b32 v64, v68, v69 offset0:44 offset1:45
	v_mul_f32_e32 v68, v30, v66
	v_mul_f32_e32 v69, v31, v66
	ds_write2st64_b32 v64, v68, v69 offset0:46 offset1:47
	v_mul_f32_e32 v68, v0, v66
	v_mul_f32_e32 v69, v1, v66
	ds_write2st64_b32 v64, v68, v69 offset0:48 offset1:49
	v_mul_f32_e32 v68, v2, v66
	v_mul_f32_e32 v69, v3, v66
	ds_write2st64_b32 v64, v68, v69 offset0:50 offset1:51
	v_mul_f32_e32 v68, v4, v66
	v_mul_f32_e32 v69, v5, v66
	ds_write2st64_b32 v64, v68, v69 offset0:52 offset1:53
	v_mul_f32_e32 v68, v6, v66
	v_mul_f32_e32 v69, v7, v66
	ds_write2st64_b32 v64, v68, v69 offset0:54 offset1:55
	v_mul_f32_e32 v68, v8, v66
	v_mul_f32_e32 v69, v9, v66
	ds_write2st64_b32 v64, v68, v69 offset0:56 offset1:57
	v_mul_f32_e32 v68, v10, v66
	v_mul_f32_e32 v69, v11, v66
	ds_write2st64_b32 v64, v68, v69 offset0:58 offset1:59
	v_mul_f32_e32 v68, v12, v66
	v_mul_f32_e32 v69, v13, v66
	ds_write2st64_b32 v64, v68, v69 offset0:60 offset1:61
	v_mul_f32_e32 v68, v14, v66
	v_mul_f32_e32 v66, v15, v66
	ds_write2st64_b32 v64, v68, v66 offset0:62 offset1:63

.LBB0_617:
	s_or_b64 exec, exec, s[70:71]
	s_ashr_i32 s41, s40, 31
	s_lshl_b64 s[70:71], s[40:41], 10
	s_add_u32 s37, s42, s70
	s_addc_u32 s48, s43, s71
	s_lshl_b32 s3, s22, 1
	s_add_u32 s37, s37, s3
	s_addc_u32 s48, s48, 0
	s_add_u32 s60, s37, 0xab00000
	s_addc_u32 s61, s48, 0
	v_and_b32_e32 v27, 15, v18
	v_lshlrev_b64 v[32:33], 10, v[22:23]
	s_lshl_b32 s52, s22, 16
	v_lshlrev_b32_e32 v176, 4, v27
	v_lshl_add_u64 v[32:33], s[60:61], 0, v[32:33]
	s_add_u32 s37, s46, s52
	v_lshl_add_u64 v[36:37], v[32:33], 0, v[176:177]
	s_mov_b32 s7, 0x8000
	s_addc_u32 s48, s47, 0
	s_lshl_b64 s[72:73], s[40:41], 1
	v_ashrrev_i32_e32 v34, 3, v18
	v_lshl_add_u64 v[30:31], s[60:61], 0, v[16:17]
	v_add_co_u32_e64 v32, s[40:41], s7, v36
	s_add_u32 s62, s37, s72
	v_lshl_add_u64 v[30:31], v[30:31], 0, v[176:177]
	v_addc_co_u32_e64 v33, s[40:41], 0, v37, s[40:41]
	v_ashrrev_i32_e32 v35, 31, v34
	s_addc_u32 s63, s48, s73
	v_and_b32_e32 v29, 7, v18
	global_load_dwordx4 v[96:99], v[30:31], off
	global_load_dwordx4 v[100:103], v[32:33], off
	v_lshlrev_b64 v[32:33], 16, v[34:35]
	v_lshl_add_u64 v[38:39], s[62:63], 0, v[32:33]
	v_lshlrev_b32_e32 v30, 4, v29
	v_mov_b32_e32 v31, v177
	v_lshl_add_u64 v[38:39], v[38:39], 0, v[30:31]
	s_mov_b32 s7, 0xcb00000
	s_mov_b64 s[14:15], 0xcb00000
	v_add_co_u32_e64 v42, s[40:41], s7, v38
	v_lshl_add_u64 v[40:41], v[38:39], 0, s[14:15]
	s_nop 0
	v_addc_co_u32_e64 v43, s[40:41], 0, v39, s[40:41]
	s_mov_b64 s[14:15], 0xcf00000
	s_mov_b32 s7, 0xcf00000
	v_lshl_add_u64 v[44:45], v[38:39], 0, s[14:15]
	v_add_co_u32_e64 v38, s[40:41], s7, v38
	v_readlane_b32 s7, v255, 23
	s_nop 0
	v_addc_co_u32_e64 v39, s[40:41], 0, v39, s[40:41]
	v_add_co_u32_e64 v46, s[40:41], s9, v36
	s_nop 1
	v_addc_co_u32_e64 v47, s[40:41], 0, v37, s[40:41]
	v_add_co_u32_e64 v36, s[40:41], s10, v36
	s_nop 1
	v_addc_co_u32_e64 v37, s[40:41], 0, v37, s[40:41]
	global_load_dwordx4 v[104:107], v[46:47], off
	global_load_dwordx4 v[108:111], v[36:37], off
	global_load_dwordx4 v[120:123], v[42:43], off
	global_load_dwordx4 v[112:115], v[40:41], off offset:128
	global_load_dwordx4 v[124:127], v[38:39], off
	global_load_dwordx4 v[116:119], v[44:45], off offset:128
	v_add_u32_e32 v36, s7, v20
	v_mul_lo_u32 v20, v22, s12
	v_add_u32_e32 v22, v36, v20
	s_waitcnt vmcnt(0) lgkmcnt(0)
	v_lshlrev_b32_e32 v84, 2, v18
	v_add_u32_e32 v84, 0x1ac00, v84
	ds_write_b32 v84, v88
	v_lshlrev_b32_e32 v85, 2, v85
	v_add_u32_e32 v85, 0x1ac00, v85
	ds_write_b32 v85, v89
	ds_write_b128 v22, v[4:7]
	v_mad_u64_u32 v[4:5], s[40:41], v24, s12, v[36:37]
	ds_write_b128 v4, v[0:3]
	v_mad_u64_u32 v[0:1], s[40:41], v26, s12, v[36:37]
	ds_write_b128 v0, v[12:15]
	v_mad_u64_u32 v[0:1], s[40:41], v28, s12, v[36:37]
	ds_write_b128 v0, v[8:11]
	v_lshl_add_u32 v0, v18, 2, 0
	v_add_u32_e32 v1, 0x11800, v0
	ds_write_b32 v1, v21
	s_and_saveexec_b64 s[40:41], vcc
	ds_write_b32 v1, v25 offset:2048
	s_or_b64 exec, exec, s[40:41]
	s_and_saveexec_b64 s[40:41], s[0:1]
	v_add_u32_e32 v0, 0x1a900, v0
	ds_write_b32 v0, v19
	s_or_b64 exec, exec, s[40:41]
	s_ashr_i32 s60, s58, 8
	s_lshl_b32 s40, s60, 7
	s_bfe_u32 s61, s58, 0x20006
	s_add_i32 s0, s40, 0
	s_lshr_b32 s59, s58, 6
	v_and_b32_e32 v2, 31, v18
	s_lshl_b32 s37, s61, 5
	s_add_i32 s0, s0, 0x12100
	v_or_b32_e32 v1, s37, v2
	v_mov_b32_e32 v3, s0
	s_and_b64 s[0:1], s[68:69], exec
	v_lshlrev_b32_e32 v0, 3, v18
	v_mad_u32_u24 v3, v1, s12, v3
	v_add_u32_e32 v1, 0, v20
	s_movk_i32 s0, 0x90
	v_and_b32_e32 v0, 8, v0
	v_add_u32_e32 v239, v1, v176
	v_mul_lo_u32 v1, v34, s0
	v_and_or_b32 v0, v30, s8, v0
	v_add_u32_e32 v1, 0, v1
	s_mul_i32 s0, s60, 0x410
	v_bfe_u32 v236, v18, 5, 1
	s_cselect_b32 s62, 32, 64
	v_add_u32_e32 v240, v1, v0
	s_add_i32 s63, s0, 0
	s_or_b32 s69, s37, s78
	v_mad_u32_u24 v0, v2, s12, 0
	v_lshlrev_b32_e32 v1, 7, v2
	v_lshlrev_b32_e32 v237, 4, v236
	s_add_i32 s63, s63, 0x11800
	v_add_u32_e32 v4, s40, v0
	v_sub_u32_e32 v0, v0, v1
	s_add_i32 s68, s69, 0x9f
	s_addk_i32 s69, 0x5f
	v_add_u32_e32 v243, v0, v237
	v_lshl_add_u64 v[0:1], s[52:53], 0, v[32:33]
	v_mov_b32_e32 v31, v177
	s_add_u32 s0, s46, s72
	v_lshl_add_u64 v[0:1], v[0:1], 0, v[30:31]
	s_addc_u32 s1, s47, s73
	v_lshl_add_u64 v[0:1], s[0:1], 0, v[0:1]
	s_mov_b64 s[0:1], 0xcf00180
	v_lshl_add_u64 v[190:191], v[0:1], 0, s[0:1]
	s_lshl_b32 s0, s77, 3
	s_and_b32 s0, s0, 0x300
	s_add_u32 s0, s0, s70
	s_addc_u32 s1, 0, s71
	v_lshl_add_u64 v[0:1], s[0:1], 0, v[16:17]
	v_lshl_add_u64 v[0:1], v[0:1], 0, v[176:177]
	v_lshlrev_b32_e32 v235, 2, v236
	v_lshl_add_u64 v[0:1], s[42:43], 0, v[0:1]
	s_mov_b64 s[0:1], 0xab38000
	v_lshl_add_u64 v[192:193], v[0:1], 0, s[0:1]
	v_sub_u32_e32 v0, v235, v2
	v_subrev_u32_e32 v0, s37, v0
	s_add_i32 s0, s37, s78
	v_mov_b32_e32 v248, 0
	v_lshlrev_b32_e32 v233, 3, v27
	v_and_b32_e32 v234, 63, v18
	v_add_u32_e32 v241, 0x8800, v240
	v_add_u32_e32 v242, 0xa800, v240
	v_mul_u32_u24_e32 v238, 0x110, v2
	v_add_u32_e32 v244, 0xd000, v243
	s_mov_b32 s22, 3
	v_subrev_u32_e32 v245, s78, v0
	s_mov_b32 s42, 0
	s_sub_i32 s43, 0, s0
	v_add_u32_e32 v246, v4, v237
	v_add_u32_e32 v247, v3, v237
	v_mov_b32_e32 v0, 0
	v_mov_b32_e32 v1, v248
	v_mov_b32_e32 v2, v248
	v_mov_b32_e32 v3, v248
	v_mov_b32_e32 v4, v248
	v_mov_b32_e32 v5, v248
	v_mov_b32_e32 v6, v248
	v_mov_b32_e32 v7, v248
	v_mov_b32_e32 v8, v248
	v_mov_b32_e32 v9, v248
	v_mov_b32_e32 v10, v248
	v_mov_b32_e32 v11, v248
	v_mov_b32_e32 v12, v248
	v_mov_b32_e32 v13, v248
	v_mov_b32_e32 v14, v248
	v_mov_b32_e32 v15, v248
	v_mov_b32_e32 v16, 0
	v_mov_b32_e32 v17, v248
	v_mov_b32_e32 v18, v248
	v_mov_b32_e32 v19, v248
	v_mov_b32_e32 v20, v248
	v_mov_b32_e32 v21, v248
	v_mov_b32_e32 v22, v248
	v_mov_b32_e32 v23, v248
	v_mov_b32_e32 v24, v248
	v_mov_b32_e32 v25, v248
	v_mov_b32_e32 v26, v248
	v_mov_b32_e32 v27, v248
	v_mov_b32_e32 v28, v248
	v_mov_b32_e32 v29, v248
	v_mov_b32_e32 v30, v248
	v_mov_b32_e32 v31, v248
	v_mov_b32_e32 v32, 0
	v_mov_b32_e32 v33, v248
	v_mov_b32_e32 v34, v248
	v_mov_b32_e32 v35, v248
	v_mov_b32_e32 v36, v248
	v_mov_b32_e32 v37, v248
	v_mov_b32_e32 v38, v248
	v_mov_b32_e32 v39, v248
	v_mov_b32_e32 v40, v248
	v_mov_b32_e32 v41, v248
	v_mov_b32_e32 v42, v248
	v_mov_b32_e32 v43, v248
	v_mov_b32_e32 v44, v248
	v_mov_b32_e32 v45, v248
	v_mov_b32_e32 v46, v248
	v_mov_b32_e32 v47, v248
	v_mov_b32_e32 v48, 0
	v_mov_b32_e32 v49, v248
	v_mov_b32_e32 v50, v248
	v_mov_b32_e32 v51, v248
	v_mov_b32_e32 v52, v248
	v_mov_b32_e32 v53, v248
	v_mov_b32_e32 v54, v248
	v_mov_b32_e32 v55, v248
	v_mov_b32_e32 v56, v248
	v_mov_b32_e32 v57, v248
	v_mov_b32_e32 v58, v248
	v_mov_b32_e32 v59, v248
	v_mov_b32_e32 v60, v248
	v_mov_b32_e32 v61, v248
	v_mov_b32_e32 v62, v248
	v_mov_b32_e32 v63, v248
	s_waitcnt vmcnt(0)
	ds_write_b128 v239, v[96:99]
	ds_write_b128 v239, v[100:103] offset:8704
	ds_write2_b64 v241, v[120:121], v[122:123] offset1:2
	ds_write2_b64 v242, v[124:125], v[126:127] offset0:128 offset1:130
	ds_write_b128 v239, v[104:107] offset:17408
	ds_write_b128 v239, v[108:111] offset:26112
	s_waitcnt lgkmcnt(0)
	s_barrier
	ds_read_b128 v[222:225], v247
	ds_read_b128 v[218:221], v247 offset:32
	ds_read_b128 v[214:217], v247 offset:64
	ds_read_b128 v[210:213], v247 offset:96
	ds_read_b128 v[172:175], v246 offset:0
	ds_read_b128 v[168:171], v246 offset:32
	ds_read_b128 v[164:167], v246 offset:64
	ds_read_b128 v[160:163], v246 offset:96
	ds_read_b128 v[156:159], v246 offset:8704
	ds_read_b128 v[152:155], v246 offset:8736
	ds_read_b128 v[148:151], v246 offset:8768
	ds_read_b128 v[144:147], v246 offset:8800
	v_add_co_u32_e32 v186, vcc, 0xfffe8000, v192
	s_nop 1
	v_addc_co_u32_e32 v187, vcc, -1, v193, vcc
	global_load_dwordx4 v[104:107], v[186:187], off
	v_add_co_u32_e32 v186, vcc, 0xffff0000, v192
	s_nop 1
	v_addc_co_u32_e32 v187, vcc, -1, v193, vcc
	global_load_dwordx4 v[108:111], v[186:187], off
	s_mov_b32 s100, -1
	s_branch .LBB0_623
.LBB0_622:
	s_waitcnt lgkmcnt(8)
	s_barrier
	s_add_i32 s22, s22, 2
	s_addk_i32 s42, 0x80
	v_lshl_add_u64 v[190:191], v[190:191], 0, s[26:27]
	s_cmp_ge_u32 s46, s62
	v_lshl_add_u64 v[192:193], v[192:193], 0, s[84:85]
	s_cbranch_scc1 .LBB0_637

.LBB0_625:
	s_add_i32 s47, s43, s42
	s_setprio 1
	s_cmp_lt_u32 s42, s68
	s_cselect_b64 s[40:41], -1, 0
	s_cmpk_gt_i32 s47, 0xff41
	s_cselect_b64 s[70:71], -1, 0
	s_and_b64 s[70:71], s[40:41], s[70:71]
	s_and_b64 vcc, exec, s[70:71]
	s_cbranch_vccnz .La2t0_near
	s_and_b64 s[40:41], s[40:41], exec
	s_cselect_b32 s40, 0, 0x400
	s_add_i32 s40, s63, s40
	s_cmp_eq_u32 s40, s100
	s_cbranch_scc1 .La2t0_cb
	v_mov_b32_e32 v251, s40
	ds_read_b32 v251, v251
	s_mov_b32 s100, s40
	s_waitcnt lgkmcnt(0)
	v_mov_b32_e32 v194, v251
	v_mov_b32_e32 v195, v251
	v_mov_b32_e32 v196, v251
	v_mov_b32_e32 v197, v251
	v_mov_b32_e32 v198, v251
	v_mov_b32_e32 v199, v251
	v_mov_b32_e32 v200, v251
	v_mov_b32_e32 v201, v251
	v_mov_b32_e32 v202, v251
	v_mov_b32_e32 v203, v251
	v_mov_b32_e32 v204, v251
	v_mov_b32_e32 v205, v251
	v_mov_b32_e32 v206, v251
	v_mov_b32_e32 v207, v251
	v_mov_b32_e32 v208, v251
	v_mov_b32_e32 v209, v251
	s_nop 1
.La2t0_cb:
	v_add_u32_e32 v249, s42, v245
	ds_read_b128 v[128:131], v243 offset:44032
	ds_read_b128 v[132:135], v243 offset:44064
	ds_read_b128 v[136:139], v243 offset:48640
	ds_read_b128 v[140:143], v243 offset:48672
	s_cmp_eq_u64 s[0:1], 0
	s_waitcnt lgkmcnt(11)
	v_mfma_f32_32x32x16_bf16 v[64:79], v[172:175], v[222:225], v[194:209]
	s_cbranch_scc1 .La2t0_nl0
	v_add_co_u32_e32 v186, vcc, 0xffff8000, v192
	s_nop 1
	v_addc_co_u32_e32 v187, vcc, -1, v193, vcc
	global_load_dwordx4 v[96:99], v[186:187], off
.La2t0_nl0:
	s_waitcnt lgkmcnt(10)
	v_mfma_f32_32x32x16_bf16 v[64:79], v[168:171], v[218:221], v[64:79]
	s_cbranch_scc1 .La2t0_nl1
	global_load_dwordx4 v[100:103], v[192:193], off

.La2t0_near:
	v_add_u32_e32 v249, s42, v245
	s_mul_i32 s101, s60, 0x704
	s_add_i32 s101, s101, 0x1af80
	v_lshl_add_u32 v251, v249, 2, s101
	ds_read_b32 v64, v251 offset:0
	ds_read_b32 v65, v251 offset:4
	ds_read_b32 v66, v251 offset:8
	ds_read_b32 v67, v251 offset:12
	ds_read_b32 v68, v251 offset:32
	ds_read_b32 v69, v251 offset:36
	ds_read_b32 v70, v251 offset:40
	ds_read_b32 v71, v251 offset:44
	ds_read_b32 v72, v251 offset:64
	ds_read_b32 v73, v251 offset:68
	ds_read_b32 v74, v251 offset:72
	ds_read_b32 v75, v251 offset:76
	ds_read_b32 v76, v251 offset:96
	ds_read_b32 v77, v251 offset:100
	ds_read_b32 v78, v251 offset:104
	ds_read_b32 v79, v251 offset:108
	ds_read_b32 v80, v251 offset:128
	ds_read_b32 v81, v251 offset:132
	ds_read_b32 v82, v251 offset:136
	ds_read_b32 v83, v251 offset:140
	ds_read_b32 v84, v251 offset:160
	ds_read_b32 v85, v251 offset:164
	ds_read_b32 v86, v251 offset:168
	ds_read_b32 v87, v251 offset:172
	ds_read_b32 v88, v251 offset:192
	ds_read_b32 v89, v251 offset:196
	ds_read_b32 v90, v251 offset:200
	ds_read_b32 v91, v251 offset:204
	ds_read_b32 v92, v251 offset:224
	ds_read_b32 v93, v251 offset:228
	ds_read_b32 v94, v251 offset:232
	ds_read_b32 v95, v251 offset:236
	s_waitcnt lgkmcnt(0)
	ds_read_b128 v[128:131], v243 offset:44032
	ds_read_b128 v[132:135], v243 offset:44064
	ds_read_b128 v[136:139], v243 offset:48640
	ds_read_b128 v[140:143], v243 offset:48672
	s_cmp_eq_u64 s[0:1], 0
	v_mfma_f32_32x32x16_bf16 v[64:79], v[172:175], v[222:225], v[64:79]
	s_cbranch_scc1 .La2t0n_nl0
	v_add_co_u32_e32 v186, vcc, 0xffff8000, v192
	s_nop 1
	v_addc_co_u32_e32 v187, vcc, -1, v193, vcc
	global_load_dwordx4 v[96:99], v[186:187], off
.La2t0n_nl0:
	v_mfma_f32_32x32x16_bf16 v[64:79], v[168:171], v[218:221], v[64:79]
	s_cbranch_scc1 .La2t0n_nl1
	global_load_dwordx4 v[100:103], v[192:193], off

.La2t0_pw:
	s_waitcnt lgkmcnt(8)
	s_barrier
	s_cmp_ge_u32 s22, s62
	s_cbranch_scc1 .LBB0_631
.LBB0_631:
	s_setprio 1
	s_cmp_lt_u32 s42, s69
	s_cselect_b64 s[40:41], -1, 0
	s_cmpk_gt_i32 s47, 0xff01
	s_cselect_b64 s[70:71], -1, 0
	s_and_b64 s[70:71], s[40:41], s[70:71]
	s_and_b64 vcc, exec, s[70:71]
	s_cbranch_vccnz .La2t1_near
	s_and_b64 s[40:41], s[40:41], exec
	s_cselect_b32 s40, 0, 0x400
	s_add_i32 s40, s63, s40
	s_cmp_eq_u32 s40, s100
	s_cbranch_scc1 .La2t1_cb
	v_mov_b32_e32 v251, s40
	ds_read_b32 v251, v251
	s_mov_b32 s100, s40
	s_waitcnt lgkmcnt(0)
	v_mov_b32_e32 v194, v251
	v_mov_b32_e32 v195, v251
	v_mov_b32_e32 v196, v251
	v_mov_b32_e32 v197, v251
	v_mov_b32_e32 v198, v251
	v_mov_b32_e32 v199, v251
	v_mov_b32_e32 v200, v251
	v_mov_b32_e32 v201, v251
	v_mov_b32_e32 v202, v251
	v_mov_b32_e32 v203, v251
	v_mov_b32_e32 v204, v251
	v_mov_b32_e32 v205, v251
	v_mov_b32_e32 v206, v251
	v_mov_b32_e32 v207, v251
	v_mov_b32_e32 v208, v251
	v_mov_b32_e32 v209, v251
	s_nop 1
.La2t1_cb:
	ds_read_b128 v[128:131], v243 offset:62464
	ds_read_b128 v[132:135], v243 offset:62496
	ds_read_b128 v[136:139], v244 offset:13824
	ds_read_b128 v[140:143], v244 offset:13856
	s_cmp_eq_u64 s[0:1], 0
	s_waitcnt lgkmcnt(11)
	v_mfma_f32_32x32x16_bf16 v[64:79], v[172:175], v[222:225], v[194:209]
	s_cbranch_scc1 .La2t1_nl0
	v_add_co_u32_e32 v186, vcc, 0x8000, v192
	s_nop 1
	v_addc_co_u32_e32 v187, vcc, 0, v193, vcc
	global_load_dwordx4 v[104:107], v[186:187], off
.La2t1_nl0:
	s_waitcnt lgkmcnt(10)
	v_mfma_f32_32x32x16_bf16 v[64:79], v[168:171], v[218:221], v[64:79]
	s_cbranch_scc1 .La2t1_nl1
	v_add_co_u32_e32 v186, vcc, 0x10000, v192
	s_nop 1
	v_addc_co_u32_e32 v187, vcc, 0, v193, vcc
	global_load_dwordx4 v[108:111], v[186:187], off

.La2t1_nl3:
	s_waitcnt lgkmcnt(7)
	v_mfma_f32_32x32x16_bf16 v[80:95], v[156:159], v[222:225], v[194:209]
	s_nop 11
	v_exp_f32_e32 v64, v64
	v_exp_f32_e32 v65, v65
	v_exp_f32_e32 v66, v66
	v_exp_f32_e32 v67, v67
	v_exp_f32_e32 v68, v68
	v_exp_f32_e32 v69, v69
	s_waitcnt lgkmcnt(6)
	v_mfma_f32_32x32x16_bf16 v[80:95], v[152:155], v[218:221], v[80:95]
	v_exp_f32_e32 v70, v70
	v_exp_f32_e32 v71, v71
	v_exp_f32_e32 v72, v72
	v_exp_f32_e32 v73, v73
	v_exp_f32_e32 v74, v74
	v_exp_f32_e32 v75, v75
	s_waitcnt lgkmcnt(5)
	v_mfma_f32_32x32x16_bf16 v[80:95], v[148:151], v[214:217], v[80:95]
	v_exp_f32_e32 v76, v76
	v_exp_f32_e32 v77, v77
	v_exp_f32_e32 v78, v78
	v_exp_f32_e32 v79, v79
	v_cvt_pk_bf16_f32 v160, v64, v65
	v_cvt_pk_bf16_f32 v161, v66, v67
	s_waitcnt lgkmcnt(4)
	v_mfma_f32_32x32x16_bf16 v[80:95], v[144:147], v[210:213], v[80:95]
	ds_read_b128 v[144:147], v243 offset:53248
	ds_read_b128 v[148:151], v243 offset:53280
	ds_read_b128 v[152:155], v243 offset:57856
	ds_read_b128 v[156:159], v243 offset:57888
	v_cvt_pk_bf16_f32 v162, v68, v69
	v_cvt_pk_bf16_f32 v163, v70, v71
	v_cvt_pk_bf16_f32 v164, v72, v73
	v_cvt_pk_bf16_f32 v165, v74, v75
	v_cvt_pk_bf16_f32 v166, v76, v77
	v_cvt_pk_bf16_f32 v167, v78, v79
	s_nop 4
	v_exp_f32_e32 v80, v80
	v_exp_f32_e32 v81, v81
	v_exp_f32_e32 v82, v82
	v_exp_f32_e32 v83, v83
	s_waitcnt lgkmcnt(7)
	v_mfma_f32_32x32x16_bf16 v[16:31], v[128:131], v[160:163], v[16:31]
	s_cmp_eq_u64 s[0:1], 0
	s_cbranch_scc1 .La2t1_lv_s
	s_waitcnt vmcnt(4)
	ds_write_b128 v239, v[96:99] offset:17408
	ds_write_b128 v239, v[100:103] offset:26112
	ds_write2_b64 v241, v[120:121], v[122:123] offset1:2
	ds_write2_b64 v242, v[124:125], v[126:127] offset0:128 offset1:130

.La2t1_near:
	s_mul_i32 s101, s60, 0x704
	s_add_i32 s101, s101, 0x1b080
	v_lshl_add_u32 v251, v249, 2, s101
	ds_read_b32 v64, v251 offset:0
	ds_read_b32 v65, v251 offset:4
	ds_read_b32 v66, v251 offset:8
	ds_read_b32 v67, v251 offset:12
	ds_read_b32 v68, v251 offset:32
	ds_read_b32 v69, v251 offset:36
	ds_read_b32 v70, v251 offset:40
	ds_read_b32 v71, v251 offset:44
	ds_read_b32 v72, v251 offset:64
	ds_read_b32 v73, v251 offset:68
	ds_read_b32 v74, v251 offset:72
	ds_read_b32 v75, v251 offset:76
	ds_read_b32 v76, v251 offset:96
	ds_read_b32 v77, v251 offset:100
	ds_read_b32 v78, v251 offset:104
	ds_read_b32 v79, v251 offset:108
	ds_read_b32 v80, v251 offset:128
	ds_read_b32 v81, v251 offset:132
	ds_read_b32 v82, v251 offset:136
	ds_read_b32 v83, v251 offset:140
	ds_read_b32 v84, v251 offset:160
	ds_read_b32 v85, v251 offset:164
	ds_read_b32 v86, v251 offset:168
	ds_read_b32 v87, v251 offset:172
	ds_read_b32 v88, v251 offset:192
	ds_read_b32 v89, v251 offset:196
	ds_read_b32 v90, v251 offset:200
	ds_read_b32 v91, v251 offset:204
	ds_read_b32 v92, v251 offset:224
	ds_read_b32 v93, v251 offset:228
	ds_read_b32 v94, v251 offset:232
	ds_read_b32 v95, v251 offset:236
	s_waitcnt lgkmcnt(0)
	ds_read_b128 v[128:131], v243 offset:62464
	ds_read_b128 v[132:135], v243 offset:62496
	ds_read_b128 v[136:139], v244 offset:13824
	ds_read_b128 v[140:143], v244 offset:13856
	s_cmp_eq_u64 s[0:1], 0
	v_mfma_f32_32x32x16_bf16 v[64:79], v[172:175], v[222:225], v[64:79]
	s_cbranch_scc1 .La2t1n_nl0
	v_add_co_u32_e32 v186, vcc, 0x8000, v192
	s_nop 1
	v_addc_co_u32_e32 v187, vcc, 0, v193, vcc
	global_load_dwordx4 v[104:107], v[186:187], off
.La2t1n_nl0:
	v_mfma_f32_32x32x16_bf16 v[64:79], v[168:171], v[218:221], v[64:79]
	s_cbranch_scc1 .La2t1n_nl1
	v_add_co_u32_e32 v186, vcc, 0x10000, v192
	s_nop 1
	v_addc_co_u32_e32 v187, vcc, 0, v193, vcc
	global_load_dwordx4 v[108:111], v[186:187], off

.La2t1n_nl3:
	v_mfma_f32_32x32x16_bf16 v[80:95], v[156:159], v[222:225], v[80:95]
	s_nop 11
	v_exp_f32_e32 v64, v64
	v_exp_f32_e32 v65, v65
	v_exp_f32_e32 v66, v66
	v_exp_f32_e32 v67, v67
	v_exp_f32_e32 v68, v68
	v_exp_f32_e32 v69, v69
	v_mfma_f32_32x32x16_bf16 v[80:95], v[152:155], v[218:221], v[80:95]
	v_exp_f32_e32 v70, v70
	v_exp_f32_e32 v71, v71
	v_exp_f32_e32 v72, v72
	v_exp_f32_e32 v73, v73
	v_exp_f32_e32 v74, v74
	v_exp_f32_e32 v75, v75
	v_mfma_f32_32x32x16_bf16 v[80:95], v[148:151], v[214:217], v[80:95]
	v_exp_f32_e32 v76, v76
	v_exp_f32_e32 v77, v77
	v_exp_f32_e32 v78, v78
	v_exp_f32_e32 v79, v79
	v_cvt_pk_bf16_f32 v160, v64, v65
	v_cvt_pk_bf16_f32 v161, v66, v67
	v_mfma_f32_32x32x16_bf16 v[80:95], v[144:147], v[210:213], v[80:95]
	ds_read_b128 v[144:147], v243 offset:53248
	ds_read_b128 v[148:151], v243 offset:53280
	ds_read_b128 v[152:155], v243 offset:57856
	ds_read_b128 v[156:159], v243 offset:57888
	v_cvt_pk_bf16_f32 v162, v68, v69
	v_cvt_pk_bf16_f32 v163, v70, v71
	v_cvt_pk_bf16_f32 v164, v72, v73
	v_cvt_pk_bf16_f32 v165, v74, v75
	v_cvt_pk_bf16_f32 v166, v76, v77
	v_cvt_pk_bf16_f32 v167, v78, v79
	s_nop 4
	v_exp_f32_e32 v80, v80
	v_exp_f32_e32 v81, v81
	v_exp_f32_e32 v82, v82
	v_exp_f32_e32 v83, v83
	s_waitcnt lgkmcnt(7)
	v_mfma_f32_32x32x16_bf16 v[16:31], v[128:131], v[160:163], v[16:31]
	s_cmp_eq_u64 s[0:1], 0
	s_cbranch_scc1 .La2t1n_lv_s
	s_waitcnt vmcnt(4)
	ds_write_b128 v239, v[96:99] offset:17408
	ds_write_b128 v239, v[100:103] offset:26112
	ds_write2_b64 v241, v[120:121], v[122:123] offset1:2
	ds_write2_b64 v242, v[124:125], v[126:127] offset0:128 offset1:130
